# one static s_setprio 1 for the de-phased (second-arriving) workgroup half in the eight GEMM phases, reset to 0 at phase exit
# speedup vs baseline: 1.0012x; 1.0012x over previous
.LBB0_295:
	s_mov_b32 s0, 1
	s_cmp_ge_i32 s54, s0
	s_mov_b64 s[0:1], -1
	s_cbranch_scc1 .LBB0_294
	s_and_b64 vcc, exec, s[2:3]
	s_cbranch_vccnz .LBB0_298
	s_sleep 48
	s_setprio 1

.LBB0_311:
	s_setprio 0
	s_cmp_lt_i32 s92, 4
	s_cselect_b64 s[16:17], -1, 0
	s_cmp_gt_i32 s92, 3
	s_cselect_b64 s[0:1], -1, 0
	s_cmp_lt_i32 s93, 4
	s_cselect_b64 s[2:3], -1, 0
	s_or_b64 s[0:1], s[0:1], s[2:3]
	s_and_b64 vcc, exec, s[0:1]
	s_cbranch_vccnz .LBB0_436
	s_andn2_b64 vcc, exec, s[6:7]
	s_cbranch_vccnz .LBB0_366
	s_waitcnt vmcnt(0)
	s_waitcnt lgkmcnt(0)
	s_barrier
	s_and_saveexec_b64 s[0:1], s[64:65]
	s_cbranch_execz .LBB0_365
	v_mov_b32_e32 v0, 0
	s_waitcnt vmcnt(0) expcnt(0) lgkmcnt(0)
	ds_read_b32 v2, v0 offset:59392
	ds_read_b32 v1, v0 offset:59396
	s_waitcnt lgkmcnt(1)
	v_cmp_ne_u32_e32 vcc, 0, v2
	s_cbranch_vccnz .LBB0_329
	v_readlane_b32 s2, v254, 2
	s_mul_i32 s52, s95, s2
	s_add_u32 s2, s30, 0x2954500
	s_addc_u32 s3, s31, 0
	s_add_u32 s4, s30, 0x2954700
	s_addc_u32 s5, s31, 0
	s_add_u32 s6, s30, 0x2954800
	s_addc_u32 s7, s31, 0
	s_add_u32 s8, s30, 0x2954900
	s_addc_u32 s9, s31, 0
	s_add_u32 s10, s30, 0x2954a00
	s_addc_u32 s11, s31, 0
	s_add_u32 s12, s30, 0x2954b00
	s_addc_u32 s13, s31, 0
	s_add_u32 s18, s30, 0x2954c00
	s_addc_u32 s19, s31, 0
	s_add_u32 s20, s30, 0x2954d00
	s_addc_u32 s21, s31, 0
	s_add_u32 s22, s30, 0x2954e00
	s_addc_u32 s23, s31, 0
	s_add_u32 s24, s30, 0x2954f00
	s_addc_u32 s25, s31, 0
	s_add_u32 s26, s30, 0x2955000
	s_addc_u32 s27, s31, 0
	s_add_u32 s34, s30, 0x2955100
	s_addc_u32 s35, s31, 0
	s_add_u32 s36, s30, 0x2955200
	s_addc_u32 s37, s31, 0
	s_add_u32 s38, s30, 0x2955300
	s_addc_u32 s39, s31, 0
	s_add_u32 s40, s30, 0x2955400
	s_addc_u32 s41, s31, 0
	s_add_u32 s42, s30, 0x2955500
	s_addc_u32 s43, s31, 0
	s_add_u32 s44, s30, 0x2955600
	s_mul_i32 s52, s52, s94
	s_addc_u32 s45, s31, 0
	s_mov_b32 s53, 1
	s_branch .LBB0_317

.LBB0_827:
	s_mov_b32 s6, 1
	s_cmp_ge_i32 s56, s6
	s_mov_b64 s[8:9], -1
	s_cbranch_scc1 .LBB0_826
	s_and_b64 vcc, exec, s[2:3]
	s_cbranch_vccnz .LBB0_830
	s_sleep 48
	s_setprio 1

.LBB0_847:
	s_setprio 0
	s_cmp_lt_i32 s92, 8
	s_cselect_b64 s[8:9], -1, 0
	s_cmp_gt_i32 s92, 7
	s_cselect_b64 s[2:3], -1, 0
	s_cmp_lt_i32 s93, 8
	s_cselect_b64 s[4:5], -1, 0
	s_or_b64 s[2:3], s[2:3], s[4:5]
	s_and_b64 vcc, exec, s[2:3]
	s_cbranch_vccnz .LBB0_929
	s_andn2_b64 vcc, exec, s[0:1]
	s_cbranch_vccnz .LBB0_902
	s_waitcnt vmcnt(0)
	s_waitcnt lgkmcnt(0)
	s_barrier
	s_and_saveexec_b64 s[0:1], s[64:65]
	s_cbranch_execz .LBB0_901
	v_mov_b32_e32 v0, 0
	s_waitcnt vmcnt(0) expcnt(0) lgkmcnt(0)
	ds_read_b32 v2, v0 offset:59392
	ds_read_b32 v1, v0 offset:59396
	s_waitcnt lgkmcnt(1)
	v_cmp_ne_u32_e32 vcc, 0, v2
	s_cbranch_vccnz .LBB0_865
	v_readlane_b32 s2, v254, 2
	s_mul_i32 s52, s95, s2
	s_add_u32 s2, s30, 0x2954500
	s_addc_u32 s3, s31, 0
	s_add_u32 s4, s30, 0x2954700
	s_addc_u32 s5, s31, 0
	s_add_u32 s6, s30, 0x2954800
	s_addc_u32 s7, s31, 0
	s_add_u32 s10, s30, 0x2954900
	s_addc_u32 s11, s31, 0
	s_add_u32 s12, s30, 0x2954a00
	s_addc_u32 s13, s31, 0
	s_add_u32 s16, s30, 0x2954b00
	s_addc_u32 s17, s31, 0
	s_add_u32 s18, s30, 0x2954c00
	s_addc_u32 s19, s31, 0
	s_add_u32 s20, s30, 0x2954d00
	s_addc_u32 s21, s31, 0
	s_add_u32 s22, s30, 0x2954e00
	s_addc_u32 s23, s31, 0
	s_add_u32 s24, s30, 0x2954f00
	s_addc_u32 s25, s31, 0
	s_add_u32 s26, s30, 0x2955000
	s_addc_u32 s27, s31, 0
	s_add_u32 s34, s30, 0x2955100
	s_addc_u32 s35, s31, 0
	s_add_u32 s36, s30, 0x2955200
	s_addc_u32 s37, s31, 0
	s_add_u32 s38, s30, 0x2955300
	s_addc_u32 s39, s31, 0
	s_add_u32 s40, s30, 0x2955400
	s_addc_u32 s41, s31, 0
	s_add_u32 s42, s30, 0x2955500
	s_addc_u32 s43, s31, 0
	s_add_u32 s44, s30, 0x2955600
	s_mul_i32 s52, s52, s94
	s_addc_u32 s45, s31, 0
	s_mov_b32 s53, 1
	s_branch .LBB0_853

.LBB0_985:
	s_setprio 0
	s_add_i32 s54, s54, 1
	s_mov_b64 s[10:11], 0

.LBB0_991:
	s_mov_b32 s6, 1
	s_cmp_lt_i32 s55, s6
	s_mov_b64 s[10:11], -1
	s_cbranch_scc0 .LBB0_990
	s_and_b64 vcc, exec, s[2:3]
	s_cbranch_vccnz .LBB0_994
	s_sleep 48
	s_setprio 1

.LBB0_1060:
	s_mov_b32 s0, 1
	s_cmp_ge_i32 s59, s0
	s_mov_b64 s[8:9], -1
	s_cbranch_scc1 .LBB0_1059
	s_and_b64 vcc, exec, s[2:3]
	s_cbranch_vccnz .LBB0_1063
	s_sleep 48
	s_setprio 1

.LBB0_1080:
	s_setprio 0
	s_cmp_lt_i32 s92, 11
	s_cselect_b64 s[54:55], -1, 0
	s_cmp_gt_i32 s92, 10
	s_cselect_b64 s[0:1], -1, 0
	s_cmp_lt_i32 s93, 11
	s_cselect_b64 s[2:3], -1, 0
	s_or_b64 s[0:1], s[0:1], s[2:3]
	s_and_b64 vcc, exec, s[0:1]
	s_cbranch_vccnz .LBB0_1217
	s_andn2_b64 vcc, exec, s[6:7]
	s_cbranch_vccnz .LBB0_1135
	s_waitcnt vmcnt(0)
	s_waitcnt lgkmcnt(0)
	s_barrier
	s_and_saveexec_b64 s[0:1], s[64:65]
	s_cbranch_execz .LBB0_1134
	v_mov_b32_e32 v0, 0
	s_waitcnt vmcnt(0) expcnt(0) lgkmcnt(0)
	ds_read_b32 v2, v0 offset:59392
	ds_read_b32 v1, v0 offset:59396
	s_waitcnt lgkmcnt(1)
	v_cmp_ne_u32_e32 vcc, 0, v2
	s_cbranch_vccnz .LBB0_1098
	v_readlane_b32 s2, v254, 2
	s_mul_i32 s52, s95, s2
	s_add_u32 s2, s30, 0x2954500
	s_addc_u32 s3, s31, 0
	s_add_u32 s4, s30, 0x2954700
	s_addc_u32 s5, s31, 0
	s_add_u32 s6, s30, 0x2954800
	s_addc_u32 s7, s31, 0
	s_add_u32 s10, s30, 0x2954900
	s_addc_u32 s11, s31, 0
	s_add_u32 s12, s30, 0x2954a00
	s_addc_u32 s13, s31, 0
	s_add_u32 s16, s30, 0x2954b00
	s_addc_u32 s17, s31, 0
	s_add_u32 s18, s30, 0x2954c00
	s_addc_u32 s19, s31, 0
	s_add_u32 s20, s30, 0x2954d00
	s_addc_u32 s21, s31, 0
	s_add_u32 s22, s30, 0x2954e00
	s_addc_u32 s23, s31, 0
	s_add_u32 s24, s30, 0x2954f00
	s_addc_u32 s25, s31, 0
	s_add_u32 s26, s30, 0x2955000
	s_addc_u32 s27, s31, 0
	s_add_u32 s34, s30, 0x2955100
	s_addc_u32 s35, s31, 0
	s_add_u32 s36, s30, 0x2955200
	s_addc_u32 s37, s31, 0
	s_add_u32 s38, s30, 0x2955300
	s_addc_u32 s39, s31, 0
	s_add_u32 s40, s30, 0x2955400
	s_addc_u32 s41, s31, 0
	s_add_u32 s42, s30, 0x2955500
	s_addc_u32 s43, s31, 0
	s_add_u32 s44, s30, 0x2955600
	s_mul_i32 s52, s52, s94
	s_addc_u32 s45, s31, 0
	s_mov_b32 s53, 1
	s_branch .LBB0_1086

.LBB0_1275:
	s_mov_b32 s0, 1
	s_cmp_ge_i32 s55, s0
	s_mov_b64 s[0:1], -1
	s_cbranch_scc1 .LBB0_1274
	s_and_b64 vcc, exec, s[2:3]
	s_cbranch_vccnz .LBB0_1278
	s_sleep 48
	s_setprio 1

.LBB0_1293:
	s_setprio 0
	s_cmp_lt_i32 s92, 13
	s_cselect_b64 s[16:17], -1, 0
	s_cmp_gt_i32 s92, 12
	s_cselect_b64 s[0:1], -1, 0
	s_cmp_lt_i32 s93, 13
	s_cselect_b64 s[2:3], -1, 0
	s_or_b64 s[0:1], s[0:1], s[2:3]
	s_and_b64 vcc, exec, s[0:1]
	s_cbranch_vccnz .LBB0_1419
	s_andn2_b64 vcc, exec, s[6:7]
	s_cbranch_vccnz .LBB0_1348
	s_waitcnt vmcnt(0)
	s_waitcnt lgkmcnt(0)
	s_barrier
	s_and_saveexec_b64 s[0:1], s[64:65]
	s_cbranch_execz .LBB0_1347
	v_mov_b32_e32 v0, 0
	s_waitcnt vmcnt(0) expcnt(0) lgkmcnt(0)
	ds_read_b32 v2, v0 offset:59392
	ds_read_b32 v1, v0 offset:59396
	s_waitcnt lgkmcnt(1)
	v_cmp_ne_u32_e32 vcc, 0, v2
	s_cbranch_vccnz .LBB0_1311
	v_readlane_b32 s2, v254, 2
	s_mul_i32 s52, s95, s2
	s_add_u32 s2, s30, 0x2954500
	s_addc_u32 s3, s31, 0
	s_add_u32 s4, s30, 0x2954700
	s_addc_u32 s5, s31, 0
	s_add_u32 s6, s30, 0x2954800
	s_addc_u32 s7, s31, 0
	s_add_u32 s8, s30, 0x2954900
	s_addc_u32 s9, s31, 0
	s_add_u32 s10, s30, 0x2954a00
	s_addc_u32 s11, s31, 0
	s_add_u32 s12, s30, 0x2954b00
	s_addc_u32 s13, s31, 0
	s_add_u32 s18, s30, 0x2954c00
	s_addc_u32 s19, s31, 0
	s_add_u32 s20, s30, 0x2954d00
	s_addc_u32 s21, s31, 0
	s_add_u32 s22, s30, 0x2954e00
	s_addc_u32 s23, s31, 0
	s_add_u32 s24, s30, 0x2954f00
	s_addc_u32 s25, s31, 0
	s_add_u32 s26, s30, 0x2955000
	s_addc_u32 s27, s31, 0
	s_add_u32 s34, s30, 0x2955100
	s_addc_u32 s35, s31, 0
	s_add_u32 s36, s30, 0x2955200
	s_addc_u32 s37, s31, 0
	s_add_u32 s38, s30, 0x2955300
	s_addc_u32 s39, s31, 0
	s_add_u32 s40, s30, 0x2955400
	s_addc_u32 s41, s31, 0
	s_add_u32 s42, s30, 0x2955500
	s_addc_u32 s43, s31, 0
	s_add_u32 s44, s30, 0x2955600
	s_mul_i32 s52, s52, s94
	s_addc_u32 s45, s31, 0
	s_mov_b32 s53, 1
	s_branch .LBB0_1299

.LBB0_1807:
	s_mov_b32 s6, 1
	s_cmp_ge_i32 s55, s6
	s_mov_b64 s[8:9], -1
	s_cbranch_scc1 .LBB0_1806
	s_and_b64 vcc, exec, s[2:3]
	s_cbranch_vccnz .LBB0_1810
	s_sleep 48
	s_setprio 1

.LBB0_1827:
	s_setprio 0
	s_cmp_lt_i32 s92, 17
	s_cselect_b64 s[8:9], -1, 0
	s_cmp_gt_i32 s92, 16
	s_cselect_b64 s[2:3], -1, 0
	s_cmp_lt_i32 s93, 17
	s_cselect_b64 s[4:5], -1, 0
	s_or_b64 s[2:3], s[2:3], s[4:5]
	s_and_b64 vcc, exec, s[2:3]
	s_cbranch_vccnz .LBB0_1909
	s_andn2_b64 vcc, exec, s[0:1]
	s_cbranch_vccnz .LBB0_1882
	s_waitcnt vmcnt(0)
	s_waitcnt lgkmcnt(0)
	s_barrier
	s_and_saveexec_b64 s[0:1], s[64:65]
	s_cbranch_execz .LBB0_1881
	v_mov_b32_e32 v0, 0
	s_waitcnt vmcnt(0) expcnt(0) lgkmcnt(0)
	ds_read_b32 v2, v0 offset:59392
	ds_read_b32 v1, v0 offset:59396
	s_waitcnt lgkmcnt(1)
	v_cmp_ne_u32_e32 vcc, 0, v2
	s_cbranch_vccnz .LBB0_1845
	v_readlane_b32 s2, v254, 2
	s_mul_i32 s52, s95, s2
	s_add_u32 s2, s30, 0x2954500
	s_addc_u32 s3, s31, 0
	s_add_u32 s4, s30, 0x2954700
	s_addc_u32 s5, s31, 0
	s_add_u32 s6, s30, 0x2954800
	s_addc_u32 s7, s31, 0
	s_add_u32 s10, s30, 0x2954900
	s_addc_u32 s11, s31, 0
	s_add_u32 s12, s30, 0x2954a00
	s_addc_u32 s13, s31, 0
	s_add_u32 s16, s30, 0x2954b00
	s_addc_u32 s17, s31, 0
	s_add_u32 s18, s30, 0x2954c00
	s_addc_u32 s19, s31, 0
	s_add_u32 s20, s30, 0x2954d00
	s_addc_u32 s21, s31, 0
	s_add_u32 s22, s30, 0x2954e00
	s_addc_u32 s23, s31, 0
	s_add_u32 s24, s30, 0x2954f00
	s_addc_u32 s25, s31, 0
	s_add_u32 s26, s30, 0x2955000
	s_addc_u32 s27, s31, 0
	s_add_u32 s34, s30, 0x2955100
	s_addc_u32 s35, s31, 0
	s_add_u32 s36, s30, 0x2955200
	s_addc_u32 s37, s31, 0
	s_add_u32 s38, s30, 0x2955300
	s_addc_u32 s39, s31, 0
	s_add_u32 s40, s30, 0x2955400
	s_addc_u32 s41, s31, 0
	s_add_u32 s42, s30, 0x2955500
	s_addc_u32 s43, s31, 0
	s_add_u32 s44, s30, 0x2955600
	s_mul_i32 s52, s52, s94
	s_addc_u32 s45, s31, 0
	s_mov_b32 s53, 1
	s_branch .LBB0_1833

.LBB0_2040:
	s_mov_b32 s0, 1
	s_cmp_ge_i32 s56, s0
	s_mov_b64 s[8:9], -1
	s_cbranch_scc1 .LBB0_2039
	s_and_b64 vcc, exec, s[2:3]
	s_cbranch_vccnz .LBB0_2043
	s_sleep 48
	s_setprio 1

.LBB0_2060:
	s_setprio 0
	s_cmp_gt_i32 s92, 19
	s_cselect_b64 s[0:1], -1, 0
	s_cmp_lt_i32 s93, 20
	s_cselect_b64 s[2:3], -1, 0
	s_or_b64 s[0:1], s[0:1], s[2:3]
	s_and_b64 vcc, exec, s[0:1]
	s_cbranch_vccnz .LBB0_2126
	s_andn2_b64 vcc, exec, s[6:7]
	s_cbranch_vccnz .LBB0_2115
	s_waitcnt vmcnt(0)
	s_waitcnt lgkmcnt(0)
	s_barrier
	s_and_saveexec_b64 s[0:1], s[64:65]
	s_cbranch_execz .LBB0_2114
	v_mov_b32_e32 v0, 0
	s_waitcnt vmcnt(0) expcnt(0) lgkmcnt(0)
	ds_read_b32 v2, v0 offset:59392
	ds_read_b32 v1, v0 offset:59396
	s_waitcnt lgkmcnt(1)
	v_cmp_ne_u32_e32 vcc, 0, v2
	s_cbranch_vccnz .LBB0_2078
	v_readlane_b32 s2, v254, 2
	s_mul_i32 s48, s95, s2
	s_add_u32 s2, s30, 0x2954500
	s_addc_u32 s3, s31, 0
	s_add_u32 s4, s30, 0x2954700
	s_addc_u32 s5, s31, 0
	s_add_u32 s6, s30, 0x2954800
	s_addc_u32 s7, s31, 0
	s_add_u32 s8, s30, 0x2954900
	s_addc_u32 s9, s31, 0
	s_add_u32 s10, s30, 0x2954a00
	s_addc_u32 s11, s31, 0
	s_add_u32 s12, s30, 0x2954b00
	s_addc_u32 s13, s31, 0
	s_add_u32 s14, s30, 0x2954c00
	s_addc_u32 s15, s31, 0
	s_add_u32 s16, s30, 0x2954d00
	s_addc_u32 s17, s31, 0
	s_add_u32 s18, s30, 0x2954e00
	s_addc_u32 s19, s31, 0
	s_add_u32 s20, s30, 0x2954f00
	s_addc_u32 s21, s31, 0
	s_add_u32 s22, s30, 0x2955000
	s_addc_u32 s23, s31, 0
	s_add_u32 s24, s30, 0x2955100
	s_addc_u32 s25, s31, 0
	s_add_u32 s26, s30, 0x2955200
	s_addc_u32 s27, s31, 0
	s_add_u32 s34, s30, 0x2955300
	s_addc_u32 s35, s31, 0
	s_add_u32 s36, s30, 0x2955400
	s_addc_u32 s37, s31, 0
	s_add_u32 s38, s30, 0x2955500
	s_addc_u32 s39, s31, 0
	s_add_u32 s40, s30, 0x2955600
	s_mul_i32 s48, s48, s94
	s_addc_u32 s41, s31, 0
	s_mov_b32 s49, 1
	s_branch .LBB0_2066
